# phase E branch epilogue: old-value loads issued with a lane mapping where 4 adjacent lanes read one row's 64 bytes, data moved back with ds_bpermute
# speedup vs baseline: 1.0105x; 1.0022x over previous
; __device__ __forceinline__ float bflo(unsigned u) { return __uint_as_float(u << 16); }
; __device__ __forceinline__ float bfhi(unsigned u) { return __uint_as_float(u & 0xFFFF0000u); }
; __device__ __forceinline__ void phaseE(const Params& p, int layer) {
;     ...
;         char* mb = (char*)merged + ((size_t)(brow + wr * 64) * 2048 + bcol + wc * 32) * 2;
; #pragma unroll
;         for (int ai = 0; ai < 2; ai++)
; #pragma unroll
;           for (int bj = 0; bj < 2; bj++) {
; #pragma unroll
;             for (int mh = 0; mh < 2; mh++) {
;               uint4 g4[2]; uint2 old[2][2];
; #pragma unroll
;               for (int mm = 0; mm < 2; mm++) {
;                 const int m = mh * 2 + mm;
;                 g4[mm] = *(const uint4*)(gsb + ((ai * 2 + bj) * 4 + m) * 8192 + gs_lane);
;                 if (br) {
; #pragma unroll
;                   for (int n = 0; n < 2; n++)
;                     old[mm][n] = *(const uint2*)(mb + ((size_t)(ai * 128 + m * 16) * 2048 + bj * 128 + n * 16) * 2 + lane_m);
;                 }
;               }
; #pragma unroll
;               for (int mm = 0; mm < 2; mm++) {
;                 const int m = mh * 2 + mm;
;                 const unsigned gq[4] = {g4[mm].x, g4[mm].y, g4[mm].z, g4[mm].w};
; #pragma unroll
;                 for (int n = 0; n < 2; n++) {
;                   f32x4 v = acc[ai][bj][m][n];
;                   float o0 = bflo(gq[2 * n]) * v[0], o1 = bfhi(gq[2 * n]) * v[1], o2 = bflo(gq[2 * n + 1]) * v[2], o3 = bfhi(gq[2 * n + 1]) * v[3];
;                   char* mp = mb + ((size_t)(ai * 128 + m * 16) * 2048 + bj * 128 + n * 16) * 2 + lane_m;
;                   if (br) { o0 += bflo(old[mm][n].x); o1 += bfhi(old[mm][n].x); o2 += bflo(old[mm][n].y); o3 += bfhi(old[mm][n].y); }
;                   *(uint2*)mp = make_uint2(pk2(o0, o1), pk2(o2, o3));
;                 }
;               }
.LBB0_2323:
	v_readlane_b32 s0, v253, 51
	v_readlane_b32 s1, v253, 52
	v_add_u32_e32 v165, 0x20000, v160
	v_and_b32_e32 v163, 63, v162
	v_add_u32_e32 v163, v163, v162
	v_and_b32_e32 v221, 3, v202
	v_lshrrev_b32_e32 v220, 2, v202
	v_lshl_add_u32 v221, v221, 4, v220
	v_lshlrev_b32_e32 v221, 2, v221
	ds_bpermute_b32 v220, v221, v163
	v_and_b32_e32 v221, 15, v202
	v_lshrrev_b32_e32 v222, 4, v202
	v_lshlrev_b32_e32 v222, 2, v222
	v_lshl_or_b32 v221, v221, 4, v222
	s_waitcnt lgkmcnt(0)
	s_cmp_lg_u64 s[12:13], 0
	s_nop 3
	s_cbranch_scc0 .Lbrepi_first
	ds_read_b128 v[128:131], v165
	global_load_dwordx4 v[132:135], v220, s[6:7]
	ds_read_b128 v[136:139], v165 offset:8192
	v_add_u32_e32 v210, 0x10000, v220
	global_load_dwordx4 v[140:143], v210, s[6:7]
	ds_read_b128 v[148:151], v165 offset:16384
	v_add_u32_e32 v211, 0x20000, v220
	global_load_dwordx4 v[152:155], v211, s[6:7]
	ds_read_b128 v[164:167], v165 offset:24576
	v_add_u32_e32 v210, 0x30000, v220
	global_load_dwordx4 v[168:171], v210, s[6:7]
	v_add_u32_e32 v146, 0x8000, v160
	global_load_dwordx4 v[172:175], v146, s[0:1]
	global_load_dwordx4 v[176:179], v220, s[6:7] offset:256
	v_add_u32_e32 v147, 0xa000, v160
	global_load_dwordx4 v[180:183], v147, s[0:1]
	v_add_u32_e32 v211, 0x10000, v220
	global_load_dwordx4 v[184:187], v211, s[6:7] offset:256
	v_add_u32_e32 v146, 0xc000, v160
	global_load_dwordx4 v[188:191], v146, s[0:1]
	v_add_u32_e32 v210, 0x20000, v220
	global_load_dwordx4 v[192:195], v210, s[6:7] offset:256
	v_add_u32_e32 v147, 0xe000, v160
	global_load_dwordx4 v[212:215], v147, s[0:1]
	v_add_u32_e32 v211, 0x30000, v220
	global_load_dwordx4 v[216:219], v211, s[6:7] offset:256
	s_waitcnt vmcnt(11) lgkmcnt(0)
	ds_bpermute_b32 v132, v221, v132
	ds_bpermute_b32 v133, v221, v133
	ds_bpermute_b32 v134, v221, v134
	ds_bpermute_b32 v135, v221, v135
	s_waitcnt lgkmcnt(0)
	s_nop 3
	v_permlane16_swap_b32_e32 v132, v134
	v_permlane16_swap_b32_e32 v133, v135
	s_nop 3
	v_permlane32_swap_b32_e32 v132, v134
	v_permlane32_swap_b32_e32 v133, v135
	s_nop 3
	v_lshlrev_b32_e32 v156, 16, v128
	v_and_b32_e32 v157, 0xffff0000, v128
	v_lshlrev_b32_e32 v158, 16, v129
	v_and_b32_e32 v159, 0xffff0000, v129
	v_pk_mul_f32 v[156:157], v[124:125], v[156:157]
	v_pk_mul_f32 v[158:159], v[126:127], v[158:159]
	v_lshlrev_b32_e32 v244, 16, v130
	v_and_b32_e32 v245, 0xffff0000, v130
	v_lshlrev_b32_e32 v246, 16, v131
	v_and_b32_e32 v247, 0xffff0000, v131
	v_pk_mul_f32 v[244:245], v[120:121], v[244:245]
	v_pk_mul_f32 v[246:247], v[122:123], v[246:247]
	v_lshlrev_b32_e32 v196, 16, v132
	v_and_b32_e32 v197, 0xffff0000, v132
	v_lshlrev_b32_e32 v198, 16, v133
	v_and_b32_e32 v199, 0xffff0000, v133
	v_pk_add_f32 v[156:157], v[156:157], v[196:197]
	v_pk_add_f32 v[158:159], v[158:159], v[198:199]
	v_lshlrev_b32_e32 v200, 16, v134
	v_and_b32_e32 v201, 0xffff0000, v134
	v_lshlrev_b32_e32 v204, 16, v135
	v_and_b32_e32 v205, 0xffff0000, v135
	v_pk_add_f32 v[244:245], v[244:245], v[200:201]
	v_pk_add_f32 v[246:247], v[246:247], v[204:205]
	v_cvt_pk_bf16_f32 v228, v156, v157
	v_cvt_pk_bf16_f32 v229, v158, v159
	v_cvt_pk_bf16_f32 v230, v244, v245
	v_cvt_pk_bf16_f32 v231, v246, v247
	s_nop 3
	v_permlane32_swap_b32_e32 v228, v230
	v_permlane32_swap_b32_e32 v229, v231
	s_nop 3
	v_permlane16_swap_b32_e32 v228, v230
	v_permlane16_swap_b32_e32 v229, v231
	s_nop 3
	global_store_dwordx4 v163, v[228:231], s[6:7]
	v_add_u32_e32 v146, 0x10000, v160
	global_load_dwordx4 v[128:131], v146, s[0:1]
	v_add_u32_e32 v210, 0x80000, v220
	global_load_dwordx4 v[132:135], v210, s[6:7]
	s_waitcnt vmcnt(13) lgkmcnt(0)
	ds_bpermute_b32 v140, v221, v140
	ds_bpermute_b32 v141, v221, v141
	ds_bpermute_b32 v142, v221, v142
	ds_bpermute_b32 v143, v221, v143
	s_waitcnt lgkmcnt(0)
	s_nop 3
	v_permlane16_swap_b32_e32 v140, v142
	v_permlane16_swap_b32_e32 v141, v143
	s_nop 3
	v_permlane32_swap_b32_e32 v140, v142
	v_permlane32_swap_b32_e32 v141, v143
	s_nop 3
	v_lshlrev_b32_e32 v156, 16, v136
	v_and_b32_e32 v157, 0xffff0000, v136
	v_lshlrev_b32_e32 v158, 16, v137
	v_and_b32_e32 v159, 0xffff0000, v137
	v_pk_mul_f32 v[156:157], v[116:117], v[156:157]
	v_pk_mul_f32 v[158:159], v[118:119], v[158:159]
	v_lshlrev_b32_e32 v244, 16, v138
	v_and_b32_e32 v245, 0xffff0000, v138
	v_lshlrev_b32_e32 v246, 16, v139
	v_and_b32_e32 v247, 0xffff0000, v139
	v_pk_mul_f32 v[244:245], v[112:113], v[244:245]
	v_pk_mul_f32 v[246:247], v[114:115], v[246:247]
	v_lshlrev_b32_e32 v196, 16, v140
	v_and_b32_e32 v197, 0xffff0000, v140
	v_lshlrev_b32_e32 v198, 16, v141
	v_and_b32_e32 v199, 0xffff0000, v141
	v_pk_add_f32 v[156:157], v[156:157], v[196:197]
	v_pk_add_f32 v[158:159], v[158:159], v[198:199]
	v_lshlrev_b32_e32 v200, 16, v142
	v_and_b32_e32 v201, 0xffff0000, v142
	v_lshlrev_b32_e32 v204, 16, v143
	v_and_b32_e32 v205, 0xffff0000, v143
	v_pk_add_f32 v[244:245], v[244:245], v[200:201]
	v_pk_add_f32 v[246:247], v[246:247], v[204:205]
	v_cvt_pk_bf16_f32 v232, v156, v157
	v_cvt_pk_bf16_f32 v233, v158, v159
	v_cvt_pk_bf16_f32 v234, v244, v245
	v_cvt_pk_bf16_f32 v235, v246, v247
	v_add_u32_e32 v211, 0x10000, v163
	s_nop 3
	v_permlane32_swap_b32_e32 v232, v234
	v_permlane32_swap_b32_e32 v233, v235
	s_nop 3
	v_permlane16_swap_b32_e32 v232, v234
	v_permlane16_swap_b32_e32 v233, v235
	s_nop 3
	global_store_dwordx4 v211, v[232:235], s[6:7]
	v_add_u32_e32 v147, 0x12000, v160
	global_load_dwordx4 v[136:139], v147, s[0:1]
	v_add_u32_e32 v210, 0x90000, v220
	global_load_dwordx4 v[140:143], v210, s[6:7]
	s_waitcnt vmcnt(15) lgkmcnt(0)
	ds_bpermute_b32 v152, v221, v152
	ds_bpermute_b32 v153, v221, v153
	ds_bpermute_b32 v154, v221, v154
	ds_bpermute_b32 v155, v221, v155
	s_waitcnt lgkmcnt(0)
; __device__ __forceinline__ float bflo(unsigned u) { return __uint_as_float(u << 16); }
; __device__ __forceinline__ float bfhi(unsigned u) { return __uint_as_float(u & 0xFFFF0000u); }
; __device__ __forceinline__ void phaseE(const Params& p, int layer) {
;     ...
;             for (int mh = 0; mh < 2; mh++) {
;               uint4 g4[2]; uint2 old[2][2];
; #pragma unroll
;               for (int mm = 0; mm < 2; mm++) {
;                 const int m = mh * 2 + mm;
;                 g4[mm] = *(const uint4*)(gsb + ((ai * 2 + bj) * 4 + m) * 8192 + gs_lane);
;                 if (br) {
; #pragma unroll
;                   for (int n = 0; n < 2; n++)
;                     old[mm][n] = *(const uint2*)(mb + ((size_t)(ai * 128 + m * 16) * 2048 + bj * 128 + n * 16) * 2 + lane_m);
;                 }
;               }
; #pragma unroll
;               for (int mm = 0; mm < 2; mm++) {
;                 const int m = mh * 2 + mm;
;                 const unsigned gq[4] = {g4[mm].x, g4[mm].y, g4[mm].z, g4[mm].w};
; #pragma unroll
;                 for (int n = 0; n < 2; n++) {
;                   f32x4 v = acc[ai][bj][m][n];
;                   float o0 = bflo(gq[2 * n]) * v[0], o1 = bfhi(gq[2 * n]) * v[1], o2 = bflo(gq[2 * n + 1]) * v[2], o3 = bfhi(gq[2 * n + 1]) * v[3];
;                   char* mp = mb + ((size_t)(ai * 128 + m * 16) * 2048 + bj * 128 + n * 16) * 2 + lane_m;
;                   if (br) { o0 += bflo(old[mm][n].x); o1 += bfhi(old[mm][n].x); o2 += bflo(old[mm][n].y); o3 += bfhi(old[mm][n].y); }
;                   *(uint2*)mp = make_uint2(pk2(o0, o1), pk2(o2, o3));
;                 }
;               }
	s_nop 3
	v_permlane16_swap_b32_e32 v152, v154
	v_permlane16_swap_b32_e32 v153, v155
	s_nop 3
	v_permlane32_swap_b32_e32 v152, v154
	v_permlane32_swap_b32_e32 v153, v155
	s_nop 3
	v_lshlrev_b32_e32 v156, 16, v148
	v_and_b32_e32 v157, 0xffff0000, v148
	v_lshlrev_b32_e32 v158, 16, v149
	v_and_b32_e32 v159, 0xffff0000, v149
	v_pk_mul_f32 v[156:157], v[108:109], v[156:157]
	v_pk_mul_f32 v[158:159], v[110:111], v[158:159]
	v_lshlrev_b32_e32 v244, 16, v150
	v_and_b32_e32 v245, 0xffff0000, v150
	v_lshlrev_b32_e32 v246, 16, v151
	v_and_b32_e32 v247, 0xffff0000, v151
	v_pk_mul_f32 v[244:245], v[104:105], v[244:245]
	v_pk_mul_f32 v[246:247], v[106:107], v[246:247]
	v_lshlrev_b32_e32 v196, 16, v152
	v_and_b32_e32 v197, 0xffff0000, v152
	v_lshlrev_b32_e32 v198, 16, v153
	v_and_b32_e32 v199, 0xffff0000, v153
	v_pk_add_f32 v[156:157], v[156:157], v[196:197]
	v_pk_add_f32 v[158:159], v[158:159], v[198:199]
	v_lshlrev_b32_e32 v200, 16, v154
	v_and_b32_e32 v201, 0xffff0000, v154
	v_lshlrev_b32_e32 v204, 16, v155
	v_and_b32_e32 v205, 0xffff0000, v155
	v_pk_add_f32 v[244:245], v[244:245], v[200:201]
	v_pk_add_f32 v[246:247], v[246:247], v[204:205]
	v_cvt_pk_bf16_f32 v236, v156, v157
	v_cvt_pk_bf16_f32 v237, v158, v159
	v_cvt_pk_bf16_f32 v238, v244, v245
	v_cvt_pk_bf16_f32 v239, v246, v247
	v_add_u32_e32 v211, 0x20000, v163
	s_nop 3
	v_permlane32_swap_b32_e32 v236, v238
	v_permlane32_swap_b32_e32 v237, v239
	s_nop 3
	v_permlane16_swap_b32_e32 v236, v238
	v_permlane16_swap_b32_e32 v237, v239
	s_nop 3
	global_store_dwordx4 v211, v[236:239], s[6:7]
	v_add_u32_e32 v146, 0x14000, v160
	global_load_dwordx4 v[148:151], v146, s[0:1]
	v_add_u32_e32 v210, 0xa0000, v220
	global_load_dwordx4 v[152:155], v210, s[6:7]
	s_waitcnt vmcnt(17) lgkmcnt(0)
	ds_bpermute_b32 v168, v221, v168
	ds_bpermute_b32 v169, v221, v169
	ds_bpermute_b32 v170, v221, v170
	ds_bpermute_b32 v171, v221, v171
	s_waitcnt lgkmcnt(0)
	s_nop 3
	v_permlane16_swap_b32_e32 v168, v170
	v_permlane16_swap_b32_e32 v169, v171
	s_nop 3
	v_permlane32_swap_b32_e32 v168, v170
	v_permlane32_swap_b32_e32 v169, v171
	s_nop 3
	v_lshlrev_b32_e32 v156, 16, v164
	v_and_b32_e32 v157, 0xffff0000, v164
	v_lshlrev_b32_e32 v158, 16, v165
	v_and_b32_e32 v159, 0xffff0000, v165
	v_pk_mul_f32 v[156:157], v[100:101], v[156:157]
	v_pk_mul_f32 v[158:159], v[102:103], v[158:159]
	v_lshlrev_b32_e32 v244, 16, v166
	v_and_b32_e32 v245, 0xffff0000, v166
	v_lshlrev_b32_e32 v246, 16, v167
	v_and_b32_e32 v247, 0xffff0000, v167
	v_pk_mul_f32 v[244:245], v[96:97], v[244:245]
	v_pk_mul_f32 v[246:247], v[98:99], v[246:247]
	v_lshlrev_b32_e32 v196, 16, v168
	v_and_b32_e32 v197, 0xffff0000, v168
	v_lshlrev_b32_e32 v198, 16, v169
	v_and_b32_e32 v199, 0xffff0000, v169
	v_pk_add_f32 v[156:157], v[156:157], v[196:197]
	v_pk_add_f32 v[158:159], v[158:159], v[198:199]
	v_lshlrev_b32_e32 v200, 16, v170
	v_and_b32_e32 v201, 0xffff0000, v170
	v_lshlrev_b32_e32 v204, 16, v171
	v_and_b32_e32 v205, 0xffff0000, v171
	v_pk_add_f32 v[244:245], v[244:245], v[200:201]
	v_pk_add_f32 v[246:247], v[246:247], v[204:205]
	v_cvt_pk_bf16_f32 v240, v156, v157
	v_cvt_pk_bf16_f32 v241, v158, v159
	v_cvt_pk_bf16_f32 v242, v244, v245
	v_cvt_pk_bf16_f32 v243, v246, v247
	v_add_u32_e32 v211, 0x30000, v163
	s_nop 3
	v_permlane32_swap_b32_e32 v240, v242
	v_permlane32_swap_b32_e32 v241, v243
	s_nop 3
	v_permlane16_swap_b32_e32 v240, v242
	v_permlane16_swap_b32_e32 v241, v243
	s_nop 3
	global_store_dwordx4 v211, v[240:243], s[6:7]
	v_add_u32_e32 v147, 0x16000, v160
	global_load_dwordx4 v[164:167], v147, s[0:1]
	v_add_u32_e32 v210, 0xb0000, v220
	global_load_dwordx4 v[168:171], v210, s[6:7]
	s_waitcnt vmcnt(18)
	ds_bpermute_b32 v176, v221, v176
	ds_bpermute_b32 v177, v221, v177
	ds_bpermute_b32 v178, v221, v178
	ds_bpermute_b32 v179, v221, v179
	s_waitcnt lgkmcnt(0)
	s_nop 3
	v_permlane16_swap_b32_e32 v176, v178
	v_permlane16_swap_b32_e32 v177, v179
	s_nop 3
	v_permlane32_swap_b32_e32 v176, v178
	v_permlane32_swap_b32_e32 v177, v179
	s_nop 3
	v_lshlrev_b32_e32 v156, 16, v172
	v_and_b32_e32 v157, 0xffff0000, v172
	v_lshlrev_b32_e32 v158, 16, v173
	v_and_b32_e32 v159, 0xffff0000, v173
	v_pk_mul_f32 v[156:157], v[92:93], v[156:157]
	v_pk_mul_f32 v[158:159], v[94:95], v[158:159]
	v_lshlrev_b32_e32 v244, 16, v174
	v_and_b32_e32 v245, 0xffff0000, v174
	v_lshlrev_b32_e32 v246, 16, v175
	v_and_b32_e32 v247, 0xffff0000, v175
	v_pk_mul_f32 v[244:245], v[88:89], v[244:245]
	v_pk_mul_f32 v[246:247], v[90:91], v[246:247]
	v_lshlrev_b32_e32 v196, 16, v176
	v_and_b32_e32 v197, 0xffff0000, v176
	v_lshlrev_b32_e32 v198, 16, v177
	v_and_b32_e32 v199, 0xffff0000, v177
	v_pk_add_f32 v[156:157], v[156:157], v[196:197]
	v_pk_add_f32 v[158:159], v[158:159], v[198:199]
	v_lshlrev_b32_e32 v200, 16, v178
	v_and_b32_e32 v201, 0xffff0000, v178
	v_lshlrev_b32_e32 v204, 16, v179
	v_and_b32_e32 v205, 0xffff0000, v179
	v_pk_add_f32 v[244:245], v[244:245], v[200:201]
	v_pk_add_f32 v[246:247], v[246:247], v[204:205]
	v_cvt_pk_bf16_f32 v228, v156, v157
	v_cvt_pk_bf16_f32 v229, v158, v159
	v_cvt_pk_bf16_f32 v230, v244, v245
	v_cvt_pk_bf16_f32 v231, v246, v247
	s_nop 3
	v_permlane32_swap_b32_e32 v228, v230
	v_permlane32_swap_b32_e32 v229, v231
	s_nop 3
	v_permlane16_swap_b32_e32 v228, v230
	v_permlane16_swap_b32_e32 v229, v231
	s_nop 3
	global_store_dwordx4 v163, v[228:231], s[6:7] offset:256
	v_add_u32_e32 v146, 0x18000, v160
	global_load_dwordx4 v[172:175], v146, s[0:1]
	v_add_u32_e32 v211, 0x80000, v220
	global_load_dwordx4 v[176:179], v211, s[6:7] offset:256
	s_waitcnt vmcnt(19)
	ds_bpermute_b32 v184, v221, v184
	ds_bpermute_b32 v185, v221, v185
	ds_bpermute_b32 v186, v221, v186
	ds_bpermute_b32 v187, v221, v187
	s_waitcnt lgkmcnt(0)
; __device__ __forceinline__ float bflo(unsigned u) { return __uint_as_float(u << 16); }
; __device__ __forceinline__ float bfhi(unsigned u) { return __uint_as_float(u & 0xFFFF0000u); }
; __device__ __forceinline__ void phaseE(const Params& p, int layer) {
;     ...
;             for (int mh = 0; mh < 2; mh++) {
;               uint4 g4[2]; uint2 old[2][2];
; #pragma unroll
;               for (int mm = 0; mm < 2; mm++) {
;                 const int m = mh * 2 + mm;
;                 g4[mm] = *(const uint4*)(gsb + ((ai * 2 + bj) * 4 + m) * 8192 + gs_lane);
;                 if (br) {
; #pragma unroll
;                   for (int n = 0; n < 2; n++)
;                     old[mm][n] = *(const uint2*)(mb + ((size_t)(ai * 128 + m * 16) * 2048 + bj * 128 + n * 16) * 2 + lane_m);
;                 }
;               }
; #pragma unroll
;               for (int mm = 0; mm < 2; mm++) {
;                 const int m = mh * 2 + mm;
;                 const unsigned gq[4] = {g4[mm].x, g4[mm].y, g4[mm].z, g4[mm].w};
; #pragma unroll
;                 for (int n = 0; n < 2; n++) {
;                   f32x4 v = acc[ai][bj][m][n];
;                   float o0 = bflo(gq[2 * n]) * v[0], o1 = bfhi(gq[2 * n]) * v[1], o2 = bflo(gq[2 * n + 1]) * v[2], o3 = bfhi(gq[2 * n + 1]) * v[3];
;                   char* mp = mb + ((size_t)(ai * 128 + m * 16) * 2048 + bj * 128 + n * 16) * 2 + lane_m;
;                   if (br) { o0 += bflo(old[mm][n].x); o1 += bfhi(old[mm][n].x); o2 += bflo(old[mm][n].y); o3 += bfhi(old[mm][n].y); }
;                   *(uint2*)mp = make_uint2(pk2(o0, o1), pk2(o2, o3));
;                 }
	s_nop 3
	v_permlane16_swap_b32_e32 v184, v186
	v_permlane16_swap_b32_e32 v185, v187
	s_nop 3
	v_permlane32_swap_b32_e32 v184, v186
	v_permlane32_swap_b32_e32 v185, v187
	s_nop 3
	v_lshlrev_b32_e32 v156, 16, v180
	v_and_b32_e32 v157, 0xffff0000, v180
	v_lshlrev_b32_e32 v158, 16, v181
	v_and_b32_e32 v159, 0xffff0000, v181
	v_pk_mul_f32 v[156:157], v[84:85], v[156:157]
	v_pk_mul_f32 v[158:159], v[86:87], v[158:159]
	v_lshlrev_b32_e32 v244, 16, v182
	v_and_b32_e32 v245, 0xffff0000, v182
	v_lshlrev_b32_e32 v246, 16, v183
	v_and_b32_e32 v247, 0xffff0000, v183
	v_pk_mul_f32 v[244:245], v[80:81], v[244:245]
	v_pk_mul_f32 v[246:247], v[82:83], v[246:247]
	v_lshlrev_b32_e32 v196, 16, v184
	v_and_b32_e32 v197, 0xffff0000, v184
	v_lshlrev_b32_e32 v198, 16, v185
	v_and_b32_e32 v199, 0xffff0000, v185
	v_pk_add_f32 v[156:157], v[156:157], v[196:197]
	v_pk_add_f32 v[158:159], v[158:159], v[198:199]
	v_lshlrev_b32_e32 v200, 16, v186
	v_and_b32_e32 v201, 0xffff0000, v186
	v_lshlrev_b32_e32 v204, 16, v187
	v_and_b32_e32 v205, 0xffff0000, v187
	v_pk_add_f32 v[244:245], v[244:245], v[200:201]
	v_pk_add_f32 v[246:247], v[246:247], v[204:205]
	v_cvt_pk_bf16_f32 v232, v156, v157
	v_cvt_pk_bf16_f32 v233, v158, v159
	v_cvt_pk_bf16_f32 v234, v244, v245
	v_cvt_pk_bf16_f32 v235, v246, v247
	v_add_u32_e32 v210, 0x10000, v163
	s_nop 3
	v_permlane32_swap_b32_e32 v232, v234
	v_permlane32_swap_b32_e32 v233, v235
	s_nop 3
	v_permlane16_swap_b32_e32 v232, v234
	v_permlane16_swap_b32_e32 v233, v235
	s_nop 3
	global_store_dwordx4 v210, v[232:235], s[6:7] offset:256
	v_add_u32_e32 v147, 0x1a000, v160
	global_load_dwordx4 v[180:183], v147, s[0:1]
	v_add_u32_e32 v211, 0x90000, v220
	global_load_dwordx4 v[184:187], v211, s[6:7] offset:256
	s_waitcnt vmcnt(20)
	ds_bpermute_b32 v192, v221, v192
	ds_bpermute_b32 v193, v221, v193
	ds_bpermute_b32 v194, v221, v194
	ds_bpermute_b32 v195, v221, v195
	s_waitcnt lgkmcnt(0)
	s_nop 3
	v_permlane16_swap_b32_e32 v192, v194
	v_permlane16_swap_b32_e32 v193, v195
	s_nop 3
	v_permlane32_swap_b32_e32 v192, v194
	v_permlane32_swap_b32_e32 v193, v195
	s_nop 3
	v_lshlrev_b32_e32 v156, 16, v188
	v_and_b32_e32 v157, 0xffff0000, v188
	v_lshlrev_b32_e32 v158, 16, v189
	v_and_b32_e32 v159, 0xffff0000, v189
	v_pk_mul_f32 v[156:157], v[76:77], v[156:157]
	v_pk_mul_f32 v[158:159], v[78:79], v[158:159]
	v_lshlrev_b32_e32 v244, 16, v190
	v_and_b32_e32 v245, 0xffff0000, v190
	v_lshlrev_b32_e32 v246, 16, v191
	v_and_b32_e32 v247, 0xffff0000, v191
	v_pk_mul_f32 v[244:245], v[72:73], v[244:245]
	v_pk_mul_f32 v[246:247], v[74:75], v[246:247]
	v_lshlrev_b32_e32 v196, 16, v192
	v_and_b32_e32 v197, 0xffff0000, v192
	v_lshlrev_b32_e32 v198, 16, v193
	v_and_b32_e32 v199, 0xffff0000, v193
	v_pk_add_f32 v[156:157], v[156:157], v[196:197]
	v_pk_add_f32 v[158:159], v[158:159], v[198:199]
	v_lshlrev_b32_e32 v200, 16, v194
	v_and_b32_e32 v201, 0xffff0000, v194
	v_lshlrev_b32_e32 v204, 16, v195
	v_and_b32_e32 v205, 0xffff0000, v195
	v_pk_add_f32 v[244:245], v[244:245], v[200:201]
	v_pk_add_f32 v[246:247], v[246:247], v[204:205]
	v_cvt_pk_bf16_f32 v236, v156, v157
	v_cvt_pk_bf16_f32 v237, v158, v159
	v_cvt_pk_bf16_f32 v238, v244, v245
	v_cvt_pk_bf16_f32 v239, v246, v247
	v_add_u32_e32 v210, 0x20000, v163
	s_nop 3
	v_permlane32_swap_b32_e32 v236, v238
	v_permlane32_swap_b32_e32 v237, v239
	s_nop 3
	v_permlane16_swap_b32_e32 v236, v238
	v_permlane16_swap_b32_e32 v237, v239
	s_nop 3
	global_store_dwordx4 v210, v[236:239], s[6:7] offset:256
	v_add_u32_e32 v146, 0x1c000, v160
	global_load_dwordx4 v[188:191], v146, s[0:1]
	v_add_u32_e32 v211, 0xa0000, v220
	global_load_dwordx4 v[192:195], v211, s[6:7] offset:256
	s_waitcnt vmcnt(21)
	ds_bpermute_b32 v216, v221, v216
	ds_bpermute_b32 v217, v221, v217
	ds_bpermute_b32 v218, v221, v218
	ds_bpermute_b32 v219, v221, v219
	s_waitcnt lgkmcnt(0)
	s_nop 3
	v_permlane16_swap_b32_e32 v216, v218
	v_permlane16_swap_b32_e32 v217, v219
	s_nop 3
	v_permlane32_swap_b32_e32 v216, v218
	v_permlane32_swap_b32_e32 v217, v219
	s_nop 3
	v_lshlrev_b32_e32 v156, 16, v212
	v_and_b32_e32 v157, 0xffff0000, v212
	v_lshlrev_b32_e32 v158, 16, v213
	v_and_b32_e32 v159, 0xffff0000, v213
	v_pk_mul_f32 v[156:157], v[68:69], v[156:157]
	v_pk_mul_f32 v[158:159], v[70:71], v[158:159]
	v_lshlrev_b32_e32 v244, 16, v214
	v_and_b32_e32 v245, 0xffff0000, v214
	v_lshlrev_b32_e32 v246, 16, v215
	v_and_b32_e32 v247, 0xffff0000, v215
	v_pk_mul_f32 v[244:245], v[64:65], v[244:245]
	v_pk_mul_f32 v[246:247], v[66:67], v[246:247]
	v_lshlrev_b32_e32 v196, 16, v216
	v_and_b32_e32 v197, 0xffff0000, v216
	v_lshlrev_b32_e32 v198, 16, v217
	v_and_b32_e32 v199, 0xffff0000, v217
	v_pk_add_f32 v[156:157], v[156:157], v[196:197]
	v_pk_add_f32 v[158:159], v[158:159], v[198:199]
	v_lshlrev_b32_e32 v200, 16, v218
	v_and_b32_e32 v201, 0xffff0000, v218
	v_lshlrev_b32_e32 v204, 16, v219
	v_and_b32_e32 v205, 0xffff0000, v219
	v_pk_add_f32 v[244:245], v[244:245], v[200:201]
	v_pk_add_f32 v[246:247], v[246:247], v[204:205]
	v_cvt_pk_bf16_f32 v240, v156, v157
	v_cvt_pk_bf16_f32 v241, v158, v159
	v_cvt_pk_bf16_f32 v242, v244, v245
	v_cvt_pk_bf16_f32 v243, v246, v247
	v_add_u32_e32 v210, 0x30000, v163
	s_nop 3
	v_permlane32_swap_b32_e32 v240, v242
	v_permlane32_swap_b32_e32 v241, v243
	s_nop 3
	v_permlane16_swap_b32_e32 v240, v242
	v_permlane16_swap_b32_e32 v241, v243
	s_nop 3
	global_store_dwordx4 v210, v[240:243], s[6:7] offset:256
	v_add_u32_e32 v147, 0x1e000, v160
	global_load_dwordx4 v[212:215], v147, s[0:1]
	v_add_u32_e32 v211, 0xb0000, v220
	global_load_dwordx4 v[216:219], v211, s[6:7] offset:256
	s_waitcnt vmcnt(21)
; __device__ __forceinline__ float bflo(unsigned u) { return __uint_as_float(u << 16); }
; __device__ __forceinline__ float bfhi(unsigned u) { return __uint_as_float(u & 0xFFFF0000u); }
; __device__ __forceinline__ void phaseE(const Params& p, int layer) {
;     ...
;             for (int mh = 0; mh < 2; mh++) {
;               uint4 g4[2]; uint2 old[2][2];
; #pragma unroll
;               for (int mm = 0; mm < 2; mm++) {
;                 const int m = mh * 2 + mm;
;                 g4[mm] = *(const uint4*)(gsb + ((ai * 2 + bj) * 4 + m) * 8192 + gs_lane);
;                 if (br) {
; #pragma unroll
;                   for (int n = 0; n < 2; n++)
;                     old[mm][n] = *(const uint2*)(mb + ((size_t)(ai * 128 + m * 16) * 2048 + bj * 128 + n * 16) * 2 + lane_m);
;                 }
;               }
; #pragma unroll
;               for (int mm = 0; mm < 2; mm++) {
;                 const int m = mh * 2 + mm;
;                 const unsigned gq[4] = {g4[mm].x, g4[mm].y, g4[mm].z, g4[mm].w};
; #pragma unroll
;                 for (int n = 0; n < 2; n++) {
;                   f32x4 v = acc[ai][bj][m][n];
;                   float o0 = bflo(gq[2 * n]) * v[0], o1 = bfhi(gq[2 * n]) * v[1], o2 = bflo(gq[2 * n + 1]) * v[2], o3 = bfhi(gq[2 * n + 1]) * v[3];
;                   char* mp = mb + ((size_t)(ai * 128 + m * 16) * 2048 + bj * 128 + n * 16) * 2 + lane_m;
;                   if (br) { o0 += bflo(old[mm][n].x); o1 += bfhi(old[mm][n].x); o2 += bflo(old[mm][n].y); o3 += bfhi(old[mm][n].y); }
;                   *(uint2*)mp = make_uint2(pk2(o0, o1), pk2(o2, o3));
;                 }
	ds_bpermute_b32 v132, v221, v132
	ds_bpermute_b32 v133, v221, v133
	ds_bpermute_b32 v134, v221, v134
	ds_bpermute_b32 v135, v221, v135
	s_waitcnt lgkmcnt(0)
	s_nop 3
	v_permlane16_swap_b32_e32 v132, v134
	v_permlane16_swap_b32_e32 v133, v135
	s_nop 3
	v_permlane32_swap_b32_e32 v132, v134
	v_permlane32_swap_b32_e32 v133, v135
	s_nop 3
	v_lshlrev_b32_e32 v156, 16, v128
	v_and_b32_e32 v157, 0xffff0000, v128
	v_lshlrev_b32_e32 v158, 16, v129
	v_and_b32_e32 v159, 0xffff0000, v129
	v_pk_mul_f32 v[156:157], v[60:61], v[156:157]
	v_pk_mul_f32 v[158:159], v[62:63], v[158:159]
	v_lshlrev_b32_e32 v244, 16, v130
	v_and_b32_e32 v245, 0xffff0000, v130
	v_lshlrev_b32_e32 v246, 16, v131
	v_and_b32_e32 v247, 0xffff0000, v131
	v_pk_mul_f32 v[244:245], v[56:57], v[244:245]
	v_pk_mul_f32 v[246:247], v[58:59], v[246:247]
	v_lshlrev_b32_e32 v196, 16, v132
	v_and_b32_e32 v197, 0xffff0000, v132
	v_lshlrev_b32_e32 v198, 16, v133
	v_and_b32_e32 v199, 0xffff0000, v133
	v_pk_add_f32 v[156:157], v[156:157], v[196:197]
	v_pk_add_f32 v[158:159], v[158:159], v[198:199]
	v_lshlrev_b32_e32 v200, 16, v134
	v_and_b32_e32 v201, 0xffff0000, v134
	v_lshlrev_b32_e32 v204, 16, v135
	v_and_b32_e32 v205, 0xffff0000, v135
	v_pk_add_f32 v[244:245], v[244:245], v[200:201]
	v_pk_add_f32 v[246:247], v[246:247], v[204:205]
	v_cvt_pk_bf16_f32 v228, v156, v157
	v_cvt_pk_bf16_f32 v229, v158, v159
	v_cvt_pk_bf16_f32 v230, v244, v245
	v_cvt_pk_bf16_f32 v231, v246, v247
	v_add_u32_e32 v210, 0x80000, v163
	s_nop 3
	v_permlane32_swap_b32_e32 v228, v230
	v_permlane32_swap_b32_e32 v229, v231
	s_nop 3
	v_permlane16_swap_b32_e32 v228, v230
	v_permlane16_swap_b32_e32 v229, v231
	s_nop 3
	global_store_dwordx4 v210, v[228:231], s[6:7]
	s_waitcnt vmcnt(19)
	ds_bpermute_b32 v140, v221, v140
	ds_bpermute_b32 v141, v221, v141
	ds_bpermute_b32 v142, v221, v142
	ds_bpermute_b32 v143, v221, v143
	s_waitcnt lgkmcnt(0)
	s_nop 3
	v_permlane16_swap_b32_e32 v140, v142
	v_permlane16_swap_b32_e32 v141, v143
	s_nop 3
	v_permlane32_swap_b32_e32 v140, v142
	v_permlane32_swap_b32_e32 v141, v143
	s_nop 3
	v_lshlrev_b32_e32 v156, 16, v136
	v_and_b32_e32 v157, 0xffff0000, v136
	v_lshlrev_b32_e32 v158, 16, v137
	v_and_b32_e32 v159, 0xffff0000, v137
	v_pk_mul_f32 v[156:157], v[52:53], v[156:157]
	v_pk_mul_f32 v[158:159], v[54:55], v[158:159]
	v_lshlrev_b32_e32 v244, 16, v138
	v_and_b32_e32 v245, 0xffff0000, v138
	v_lshlrev_b32_e32 v246, 16, v139
	v_and_b32_e32 v247, 0xffff0000, v139
	v_pk_mul_f32 v[244:245], v[48:49], v[244:245]
	v_pk_mul_f32 v[246:247], v[50:51], v[246:247]
	v_lshlrev_b32_e32 v196, 16, v140
	v_and_b32_e32 v197, 0xffff0000, v140
	v_lshlrev_b32_e32 v198, 16, v141
	v_and_b32_e32 v199, 0xffff0000, v141
	v_pk_add_f32 v[156:157], v[156:157], v[196:197]
	v_pk_add_f32 v[158:159], v[158:159], v[198:199]
	v_lshlrev_b32_e32 v200, 16, v142
	v_and_b32_e32 v201, 0xffff0000, v142
	v_lshlrev_b32_e32 v204, 16, v143
	v_and_b32_e32 v205, 0xffff0000, v143
	v_pk_add_f32 v[244:245], v[244:245], v[200:201]
	v_pk_add_f32 v[246:247], v[246:247], v[204:205]
	v_cvt_pk_bf16_f32 v232, v156, v157
	v_cvt_pk_bf16_f32 v233, v158, v159
	v_cvt_pk_bf16_f32 v234, v244, v245
	v_cvt_pk_bf16_f32 v235, v246, v247
	v_add_u32_e32 v211, 0x90000, v163
	s_nop 3
	v_permlane32_swap_b32_e32 v232, v234
	v_permlane32_swap_b32_e32 v233, v235
	s_nop 3
	v_permlane16_swap_b32_e32 v232, v234
	v_permlane16_swap_b32_e32 v233, v235
	s_nop 3
	global_store_dwordx4 v211, v[232:235], s[6:7]
	s_waitcnt vmcnt(17)
	ds_bpermute_b32 v152, v221, v152
	ds_bpermute_b32 v153, v221, v153
	ds_bpermute_b32 v154, v221, v154
	ds_bpermute_b32 v155, v221, v155
	s_waitcnt lgkmcnt(0)
	s_nop 3
	v_permlane16_swap_b32_e32 v152, v154
	v_permlane16_swap_b32_e32 v153, v155
	s_nop 3
	v_permlane32_swap_b32_e32 v152, v154
	v_permlane32_swap_b32_e32 v153, v155
	s_nop 3
	v_lshlrev_b32_e32 v156, 16, v148
	v_and_b32_e32 v157, 0xffff0000, v148
	v_lshlrev_b32_e32 v158, 16, v149
	v_and_b32_e32 v159, 0xffff0000, v149
	v_pk_mul_f32 v[156:157], v[44:45], v[156:157]
	v_pk_mul_f32 v[158:159], v[46:47], v[158:159]
	v_lshlrev_b32_e32 v244, 16, v150
	v_and_b32_e32 v245, 0xffff0000, v150
	v_lshlrev_b32_e32 v246, 16, v151
	v_and_b32_e32 v247, 0xffff0000, v151
	v_pk_mul_f32 v[244:245], v[40:41], v[244:245]
	v_pk_mul_f32 v[246:247], v[42:43], v[246:247]
	v_lshlrev_b32_e32 v196, 16, v152
	v_and_b32_e32 v197, 0xffff0000, v152
	v_lshlrev_b32_e32 v198, 16, v153
	v_and_b32_e32 v199, 0xffff0000, v153
	v_pk_add_f32 v[156:157], v[156:157], v[196:197]
	v_pk_add_f32 v[158:159], v[158:159], v[198:199]
	v_lshlrev_b32_e32 v200, 16, v154
	v_and_b32_e32 v201, 0xffff0000, v154
	v_lshlrev_b32_e32 v204, 16, v155
	v_and_b32_e32 v205, 0xffff0000, v155
	v_pk_add_f32 v[244:245], v[244:245], v[200:201]
	v_pk_add_f32 v[246:247], v[246:247], v[204:205]
	v_cvt_pk_bf16_f32 v236, v156, v157
	v_cvt_pk_bf16_f32 v237, v158, v159
	v_cvt_pk_bf16_f32 v238, v244, v245
	v_cvt_pk_bf16_f32 v239, v246, v247
	v_add_u32_e32 v210, 0xa0000, v163
	s_nop 3
	v_permlane32_swap_b32_e32 v236, v238
	v_permlane32_swap_b32_e32 v237, v239
	s_nop 3
	v_permlane16_swap_b32_e32 v236, v238
	v_permlane16_swap_b32_e32 v237, v239
	s_nop 3
	global_store_dwordx4 v210, v[236:239], s[6:7]
	s_waitcnt vmcnt(15)
	ds_bpermute_b32 v168, v221, v168
	ds_bpermute_b32 v169, v221, v169
	ds_bpermute_b32 v170, v221, v170
	ds_bpermute_b32 v171, v221, v171
	s_waitcnt lgkmcnt(0)
; __device__ __forceinline__ float bflo(unsigned u) { return __uint_as_float(u << 16); }
; __device__ __forceinline__ float bfhi(unsigned u) { return __uint_as_float(u & 0xFFFF0000u); }
; __device__ __forceinline__ void phaseE(const Params& p, int layer) {
;     ...
;             for (int mh = 0; mh < 2; mh++) {
;               uint4 g4[2]; uint2 old[2][2];
; #pragma unroll
;               for (int mm = 0; mm < 2; mm++) {
;                 const int m = mh * 2 + mm;
;                 g4[mm] = *(const uint4*)(gsb + ((ai * 2 + bj) * 4 + m) * 8192 + gs_lane);
;                 if (br) {
; #pragma unroll
;                   for (int n = 0; n < 2; n++)
;                     old[mm][n] = *(const uint2*)(mb + ((size_t)(ai * 128 + m * 16) * 2048 + bj * 128 + n * 16) * 2 + lane_m);
;                 }
;               }
; #pragma unroll
;               for (int mm = 0; mm < 2; mm++) {
;                 const int m = mh * 2 + mm;
;                 const unsigned gq[4] = {g4[mm].x, g4[mm].y, g4[mm].z, g4[mm].w};
; #pragma unroll
;                 for (int n = 0; n < 2; n++) {
;                   f32x4 v = acc[ai][bj][m][n];
;                   float o0 = bflo(gq[2 * n]) * v[0], o1 = bfhi(gq[2 * n]) * v[1], o2 = bflo(gq[2 * n + 1]) * v[2], o3 = bfhi(gq[2 * n + 1]) * v[3];
;                   char* mp = mb + ((size_t)(ai * 128 + m * 16) * 2048 + bj * 128 + n * 16) * 2 + lane_m;
;                   if (br) { o0 += bflo(old[mm][n].x); o1 += bfhi(old[mm][n].x); o2 += bflo(old[mm][n].y); o3 += bfhi(old[mm][n].y); }
;                   *(uint2*)mp = make_uint2(pk2(o0, o1), pk2(o2, o3));
;                 }
	s_nop 3
	v_permlane16_swap_b32_e32 v168, v170
	v_permlane16_swap_b32_e32 v169, v171
	s_nop 3
	v_permlane32_swap_b32_e32 v168, v170
	v_permlane32_swap_b32_e32 v169, v171
	s_nop 3
	v_lshlrev_b32_e32 v156, 16, v164
	v_and_b32_e32 v157, 0xffff0000, v164
	v_lshlrev_b32_e32 v158, 16, v165
	v_and_b32_e32 v159, 0xffff0000, v165
	v_pk_mul_f32 v[156:157], v[36:37], v[156:157]
	v_pk_mul_f32 v[158:159], v[38:39], v[158:159]
	v_lshlrev_b32_e32 v244, 16, v166
	v_and_b32_e32 v245, 0xffff0000, v166
	v_lshlrev_b32_e32 v246, 16, v167
	v_and_b32_e32 v247, 0xffff0000, v167
	v_pk_mul_f32 v[244:245], v[32:33], v[244:245]
	v_pk_mul_f32 v[246:247], v[34:35], v[246:247]
	v_lshlrev_b32_e32 v196, 16, v168
	v_and_b32_e32 v197, 0xffff0000, v168
	v_lshlrev_b32_e32 v198, 16, v169
	v_and_b32_e32 v199, 0xffff0000, v169
	v_pk_add_f32 v[156:157], v[156:157], v[196:197]
	v_pk_add_f32 v[158:159], v[158:159], v[198:199]
	v_lshlrev_b32_e32 v200, 16, v170
	v_and_b32_e32 v201, 0xffff0000, v170
	v_lshlrev_b32_e32 v204, 16, v171
	v_and_b32_e32 v205, 0xffff0000, v171
	v_pk_add_f32 v[244:245], v[244:245], v[200:201]
	v_pk_add_f32 v[246:247], v[246:247], v[204:205]
	v_cvt_pk_bf16_f32 v240, v156, v157
	v_cvt_pk_bf16_f32 v241, v158, v159
	v_cvt_pk_bf16_f32 v242, v244, v245
	v_cvt_pk_bf16_f32 v243, v246, v247
	v_add_u32_e32 v211, 0xb0000, v163
	s_nop 3
	v_permlane32_swap_b32_e32 v240, v242
	v_permlane32_swap_b32_e32 v241, v243
	s_nop 3
	v_permlane16_swap_b32_e32 v240, v242
	v_permlane16_swap_b32_e32 v241, v243
	s_nop 3
	global_store_dwordx4 v211, v[240:243], s[6:7]
	s_waitcnt vmcnt(13)
	ds_bpermute_b32 v176, v221, v176
	ds_bpermute_b32 v177, v221, v177
	ds_bpermute_b32 v178, v221, v178
	ds_bpermute_b32 v179, v221, v179
	s_waitcnt lgkmcnt(0)
	s_nop 3
	v_permlane16_swap_b32_e32 v176, v178
	v_permlane16_swap_b32_e32 v177, v179
	s_nop 3
	v_permlane32_swap_b32_e32 v176, v178
	v_permlane32_swap_b32_e32 v177, v179
	s_nop 3
	v_lshlrev_b32_e32 v156, 16, v172
	v_and_b32_e32 v157, 0xffff0000, v172
	v_lshlrev_b32_e32 v158, 16, v173
	v_and_b32_e32 v159, 0xffff0000, v173
	v_pk_mul_f32 v[156:157], v[28:29], v[156:157]
	v_pk_mul_f32 v[158:159], v[30:31], v[158:159]
	v_lshlrev_b32_e32 v244, 16, v174
	v_and_b32_e32 v245, 0xffff0000, v174
	v_lshlrev_b32_e32 v246, 16, v175
	v_and_b32_e32 v247, 0xffff0000, v175
	v_pk_mul_f32 v[244:245], v[24:25], v[244:245]
	v_pk_mul_f32 v[246:247], v[26:27], v[246:247]
	v_lshlrev_b32_e32 v196, 16, v176
	v_and_b32_e32 v197, 0xffff0000, v176
	v_lshlrev_b32_e32 v198, 16, v177
	v_and_b32_e32 v199, 0xffff0000, v177
	v_pk_add_f32 v[156:157], v[156:157], v[196:197]
	v_pk_add_f32 v[158:159], v[158:159], v[198:199]
	v_lshlrev_b32_e32 v200, 16, v178
	v_and_b32_e32 v201, 0xffff0000, v178
	v_lshlrev_b32_e32 v204, 16, v179
	v_and_b32_e32 v205, 0xffff0000, v179
	v_pk_add_f32 v[244:245], v[244:245], v[200:201]
	v_pk_add_f32 v[246:247], v[246:247], v[204:205]
	v_cvt_pk_bf16_f32 v228, v156, v157
	v_cvt_pk_bf16_f32 v229, v158, v159
	v_cvt_pk_bf16_f32 v230, v244, v245
	v_cvt_pk_bf16_f32 v231, v246, v247
	v_add_u32_e32 v210, 0x80000, v163
	s_nop 3
	v_permlane32_swap_b32_e32 v228, v230
	v_permlane32_swap_b32_e32 v229, v231
	s_nop 3
	v_permlane16_swap_b32_e32 v228, v230
	v_permlane16_swap_b32_e32 v229, v231
	s_nop 3
	global_store_dwordx4 v210, v[228:231], s[6:7] offset:256
	s_waitcnt vmcnt(11)
	ds_bpermute_b32 v184, v221, v184
	ds_bpermute_b32 v185, v221, v185
	ds_bpermute_b32 v186, v221, v186
	ds_bpermute_b32 v187, v221, v187
	s_waitcnt lgkmcnt(0)
	s_nop 3
	v_permlane16_swap_b32_e32 v184, v186
	v_permlane16_swap_b32_e32 v185, v187
	s_nop 3
	v_permlane32_swap_b32_e32 v184, v186
	v_permlane32_swap_b32_e32 v185, v187
	s_nop 3
	v_lshlrev_b32_e32 v156, 16, v180
	v_and_b32_e32 v157, 0xffff0000, v180
	v_lshlrev_b32_e32 v158, 16, v181
	v_and_b32_e32 v159, 0xffff0000, v181
	v_pk_mul_f32 v[156:157], v[20:21], v[156:157]
	v_pk_mul_f32 v[158:159], v[22:23], v[158:159]
	v_lshlrev_b32_e32 v244, 16, v182
	v_and_b32_e32 v245, 0xffff0000, v182
	v_lshlrev_b32_e32 v246, 16, v183
	v_and_b32_e32 v247, 0xffff0000, v183
	v_pk_mul_f32 v[244:245], v[16:17], v[244:245]
	v_pk_mul_f32 v[246:247], v[18:19], v[246:247]
	v_lshlrev_b32_e32 v196, 16, v184
	v_and_b32_e32 v197, 0xffff0000, v184
	v_lshlrev_b32_e32 v198, 16, v185
	v_and_b32_e32 v199, 0xffff0000, v185
	v_pk_add_f32 v[156:157], v[156:157], v[196:197]
	v_pk_add_f32 v[158:159], v[158:159], v[198:199]
	v_lshlrev_b32_e32 v200, 16, v186
	v_and_b32_e32 v201, 0xffff0000, v186
	v_lshlrev_b32_e32 v204, 16, v187
	v_and_b32_e32 v205, 0xffff0000, v187
	v_pk_add_f32 v[244:245], v[244:245], v[200:201]
	v_pk_add_f32 v[246:247], v[246:247], v[204:205]
	v_cvt_pk_bf16_f32 v232, v156, v157
	v_cvt_pk_bf16_f32 v233, v158, v159
	v_cvt_pk_bf16_f32 v234, v244, v245
	v_cvt_pk_bf16_f32 v235, v246, v247
	v_add_u32_e32 v211, 0x90000, v163
	s_nop 3
	v_permlane32_swap_b32_e32 v232, v234
	v_permlane32_swap_b32_e32 v233, v235
	s_nop 3
	v_permlane16_swap_b32_e32 v232, v234
	v_permlane16_swap_b32_e32 v233, v235
	s_nop 3
	global_store_dwordx4 v211, v[232:235], s[6:7] offset:256
	s_waitcnt vmcnt(9)
	ds_bpermute_b32 v192, v221, v192
	ds_bpermute_b32 v193, v221, v193
	ds_bpermute_b32 v194, v221, v194
	ds_bpermute_b32 v195, v221, v195
	s_waitcnt lgkmcnt(0)
; __device__ __forceinline__ float bflo(unsigned u) { return __uint_as_float(u << 16); }
; __device__ __forceinline__ float bfhi(unsigned u) { return __uint_as_float(u & 0xFFFF0000u); }
; __device__ __forceinline__ void phaseE(const Params& p, int layer) {
;     ...
;             for (int mh = 0; mh < 2; mh++) {
;               uint4 g4[2]; uint2 old[2][2];
; #pragma unroll
;               for (int mm = 0; mm < 2; mm++) {
;                 const int m = mh * 2 + mm;
;                 g4[mm] = *(const uint4*)(gsb + ((ai * 2 + bj) * 4 + m) * 8192 + gs_lane);
;                 if (br) {
; #pragma unroll
;                   for (int n = 0; n < 2; n++)
;                     old[mm][n] = *(const uint2*)(mb + ((size_t)(ai * 128 + m * 16) * 2048 + bj * 128 + n * 16) * 2 + lane_m);
;                 }
;               }
; #pragma unroll
;               for (int mm = 0; mm < 2; mm++) {
;                 const int m = mh * 2 + mm;
;                 const unsigned gq[4] = {g4[mm].x, g4[mm].y, g4[mm].z, g4[mm].w};
; #pragma unroll
;                 for (int n = 0; n < 2; n++) {
;                   f32x4 v = acc[ai][bj][m][n];
;                   float o0 = bflo(gq[2 * n]) * v[0], o1 = bfhi(gq[2 * n]) * v[1], o2 = bflo(gq[2 * n + 1]) * v[2], o3 = bfhi(gq[2 * n + 1]) * v[3];
;                   char* mp = mb + ((size_t)(ai * 128 + m * 16) * 2048 + bj * 128 + n * 16) * 2 + lane_m;
;                   if (br) { o0 += bflo(old[mm][n].x); o1 += bfhi(old[mm][n].x); o2 += bflo(old[mm][n].y); o3 += bfhi(old[mm][n].y); }
;                   *(uint2*)mp = make_uint2(pk2(o0, o1), pk2(o2, o3));
;                 }
	s_nop 3
	v_permlane16_swap_b32_e32 v192, v194
	v_permlane16_swap_b32_e32 v193, v195
	s_nop 3
	v_permlane32_swap_b32_e32 v192, v194
	v_permlane32_swap_b32_e32 v193, v195
	s_nop 3
	v_lshlrev_b32_e32 v156, 16, v188
	v_and_b32_e32 v157, 0xffff0000, v188
	v_lshlrev_b32_e32 v158, 16, v189
	v_and_b32_e32 v159, 0xffff0000, v189
	v_pk_mul_f32 v[156:157], v[12:13], v[156:157]
	v_pk_mul_f32 v[158:159], v[14:15], v[158:159]
	v_lshlrev_b32_e32 v244, 16, v190
	v_and_b32_e32 v245, 0xffff0000, v190
	v_lshlrev_b32_e32 v246, 16, v191
	v_and_b32_e32 v247, 0xffff0000, v191
	v_pk_mul_f32 v[244:245], v[8:9], v[244:245]
	v_pk_mul_f32 v[246:247], v[10:11], v[246:247]
	v_lshlrev_b32_e32 v196, 16, v192
	v_and_b32_e32 v197, 0xffff0000, v192
	v_lshlrev_b32_e32 v198, 16, v193
	v_and_b32_e32 v199, 0xffff0000, v193
	v_pk_add_f32 v[156:157], v[156:157], v[196:197]
	v_pk_add_f32 v[158:159], v[158:159], v[198:199]
	v_lshlrev_b32_e32 v200, 16, v194
	v_and_b32_e32 v201, 0xffff0000, v194
	v_lshlrev_b32_e32 v204, 16, v195
	v_and_b32_e32 v205, 0xffff0000, v195
	v_pk_add_f32 v[244:245], v[244:245], v[200:201]
	v_pk_add_f32 v[246:247], v[246:247], v[204:205]
	v_cvt_pk_bf16_f32 v236, v156, v157
	v_cvt_pk_bf16_f32 v237, v158, v159
	v_cvt_pk_bf16_f32 v238, v244, v245
	v_cvt_pk_bf16_f32 v239, v246, v247
	v_add_u32_e32 v210, 0xa0000, v163
	s_nop 3
	v_permlane32_swap_b32_e32 v236, v238
	v_permlane32_swap_b32_e32 v237, v239
	s_nop 3
	v_permlane16_swap_b32_e32 v236, v238
	v_permlane16_swap_b32_e32 v237, v239
	s_nop 3
	global_store_dwordx4 v210, v[236:239], s[6:7] offset:256
	s_waitcnt vmcnt(7)
	ds_bpermute_b32 v216, v221, v216
	ds_bpermute_b32 v217, v221, v217
	ds_bpermute_b32 v218, v221, v218
	ds_bpermute_b32 v219, v221, v219
	s_waitcnt lgkmcnt(0)
	s_nop 3
	v_permlane16_swap_b32_e32 v216, v218
	v_permlane16_swap_b32_e32 v217, v219
	s_nop 3
	v_permlane32_swap_b32_e32 v216, v218
	v_permlane32_swap_b32_e32 v217, v219
	s_nop 3
	v_lshlrev_b32_e32 v156, 16, v212
	v_and_b32_e32 v157, 0xffff0000, v212
	v_lshlrev_b32_e32 v158, 16, v213
	v_and_b32_e32 v159, 0xffff0000, v213
	v_pk_mul_f32 v[156:157], v[4:5], v[156:157]
	v_pk_mul_f32 v[158:159], v[6:7], v[158:159]
	v_lshlrev_b32_e32 v244, 16, v214
	v_and_b32_e32 v245, 0xffff0000, v214
	v_lshlrev_b32_e32 v246, 16, v215
	v_and_b32_e32 v247, 0xffff0000, v215
	v_pk_mul_f32 v[244:245], v[0:1], v[244:245]
	v_pk_mul_f32 v[246:247], v[2:3], v[246:247]
	v_lshlrev_b32_e32 v196, 16, v216
	v_and_b32_e32 v197, 0xffff0000, v216
	v_lshlrev_b32_e32 v198, 16, v217
	v_and_b32_e32 v199, 0xffff0000, v217
	v_pk_add_f32 v[156:157], v[156:157], v[196:197]
	v_pk_add_f32 v[158:159], v[158:159], v[198:199]
	v_lshlrev_b32_e32 v200, 16, v218
	v_and_b32_e32 v201, 0xffff0000, v218
	v_lshlrev_b32_e32 v204, 16, v219
	v_and_b32_e32 v205, 0xffff0000, v219
	v_pk_add_f32 v[244:245], v[244:245], v[200:201]
	v_pk_add_f32 v[246:247], v[246:247], v[204:205]
	v_cvt_pk_bf16_f32 v240, v156, v157
	v_cvt_pk_bf16_f32 v241, v158, v159
	v_cvt_pk_bf16_f32 v242, v244, v245
	v_cvt_pk_bf16_f32 v243, v246, v247
	v_add_u32_e32 v211, 0xb0000, v163
	s_nop 3
	v_permlane32_swap_b32_e32 v240, v242
	v_permlane32_swap_b32_e32 v241, v243
	s_nop 3
	v_permlane16_swap_b32_e32 v240, v242
	v_permlane16_swap_b32_e32 v241, v243
	s_nop 3
	global_store_dwordx4 v211, v[240:243], s[6:7] offset:256
	s_branch .LBB0_2313
.Lbrepi_first:
	ds_read_b128 v[128:131], v165
	ds_read_b128 v[136:139], v165 offset:8192
	ds_read_b128 v[148:151], v165 offset:16384
	ds_read_b128 v[164:167], v165 offset:24576
	v_add_u32_e32 v146, 0x8000, v160
	global_load_dwordx4 v[172:175], v146, s[0:1]
	v_add_u32_e32 v147, 0xa000, v160
	global_load_dwordx4 v[180:183], v147, s[0:1]
	v_add_u32_e32 v146, 0xc000, v160
	global_load_dwordx4 v[188:191], v146, s[0:1]
	v_add_u32_e32 v147, 0xe000, v160
	global_load_dwordx4 v[212:215], v147, s[0:1]
	s_waitcnt lgkmcnt(0)
	v_lshlrev_b32_e32 v156, 16, v128
	v_and_b32_e32 v157, 0xffff0000, v128
	v_lshlrev_b32_e32 v158, 16, v129
	v_and_b32_e32 v159, 0xffff0000, v129
	v_pk_mul_f32 v[156:157], v[124:125], v[156:157]
	v_pk_mul_f32 v[158:159], v[126:127], v[158:159]
	v_lshlrev_b32_e32 v244, 16, v130
	v_and_b32_e32 v245, 0xffff0000, v130
	v_lshlrev_b32_e32 v246, 16, v131
	v_and_b32_e32 v247, 0xffff0000, v131
	v_pk_mul_f32 v[244:245], v[120:121], v[244:245]
	v_pk_mul_f32 v[246:247], v[122:123], v[246:247]
	v_cvt_pk_bf16_f32 v228, v156, v157
	v_cvt_pk_bf16_f32 v229, v158, v159
	v_cvt_pk_bf16_f32 v230, v244, v245
	v_cvt_pk_bf16_f32 v231, v246, v247
	s_nop 3
	v_permlane32_swap_b32_e32 v228, v230
	v_permlane32_swap_b32_e32 v229, v231
	s_nop 3
	v_permlane16_swap_b32_e32 v228, v230
	v_permlane16_swap_b32_e32 v229, v231
	s_nop 3
	global_store_dwordx4 v163, v[228:231], s[6:7]
	v_add_u32_e32 v146, 0x10000, v160
	global_load_dwordx4 v[128:131], v146, s[0:1]
	s_waitcnt lgkmcnt(0)
	v_lshlrev_b32_e32 v156, 16, v136
	v_and_b32_e32 v157, 0xffff0000, v136
	v_lshlrev_b32_e32 v158, 16, v137
	v_and_b32_e32 v159, 0xffff0000, v137
	v_pk_mul_f32 v[156:157], v[116:117], v[156:157]
	v_pk_mul_f32 v[158:159], v[118:119], v[158:159]
	v_lshlrev_b32_e32 v244, 16, v138
	v_and_b32_e32 v245, 0xffff0000, v138
	v_lshlrev_b32_e32 v246, 16, v139
	v_and_b32_e32 v247, 0xffff0000, v139
	v_pk_mul_f32 v[244:245], v[112:113], v[244:245]
	v_pk_mul_f32 v[246:247], v[114:115], v[246:247]
	v_cvt_pk_bf16_f32 v232, v156, v157
	v_cvt_pk_bf16_f32 v233, v158, v159
	v_cvt_pk_bf16_f32 v234, v244, v245
	v_cvt_pk_bf16_f32 v235, v246, v247
	v_add_u32_e32 v210, 0x10000, v163
	s_nop 3
	v_permlane32_swap_b32_e32 v232, v234
	v_permlane32_swap_b32_e32 v233, v235
	s_nop 3
	v_permlane16_swap_b32_e32 v232, v234
	v_permlane16_swap_b32_e32 v233, v235
	s_nop 3
	global_store_dwordx4 v210, v[232:235], s[6:7]
	v_add_u32_e32 v147, 0x12000, v160
	global_load_dwordx4 v[136:139], v147, s[0:1]
	s_waitcnt lgkmcnt(0)
; __device__ __forceinline__ float bflo(unsigned u) { return __uint_as_float(u << 16); }
; __device__ __forceinline__ float bfhi(unsigned u) { return __uint_as_float(u & 0xFFFF0000u); }
; __device__ __forceinline__ void phaseE(const Params& p, int layer) {
;     ...
; #pragma unroll
;               for (int mm = 0; mm < 2; mm++) {
;                 const int m = mh * 2 + mm;
;                 g4[mm] = *(const uint4*)(gsb + ((ai * 2 + bj) * 4 + m) * 8192 + gs_lane);
;                 if (br) {
; #pragma unroll
;                   for (int n = 0; n < 2; n++)
;                     old[mm][n] = *(const uint2*)(mb + ((size_t)(ai * 128 + m * 16) * 2048 + bj * 128 + n * 16) * 2 + lane_m);
;                 }
;               }
; #pragma unroll
;               for (int mm = 0; mm < 2; mm++) {
;                 const int m = mh * 2 + mm;
;                 const unsigned gq[4] = {g4[mm].x, g4[mm].y, g4[mm].z, g4[mm].w};
; #pragma unroll
;                 for (int n = 0; n < 2; n++) {
;                   f32x4 v = acc[ai][bj][m][n];
;                   float o0 = bflo(gq[2 * n]) * v[0], o1 = bfhi(gq[2 * n]) * v[1], o2 = bflo(gq[2 * n + 1]) * v[2], o3 = bfhi(gq[2 * n + 1]) * v[3];
;                   char* mp = mb + ((size_t)(ai * 128 + m * 16) * 2048 + bj * 128 + n * 16) * 2 + lane_m;
;                   if (br) { o0 += bflo(old[mm][n].x); o1 += bfhi(old[mm][n].x); o2 += bflo(old[mm][n].y); o3 += bfhi(old[mm][n].y); }
;                   *(uint2*)mp = make_uint2(pk2(o0, o1), pk2(o2, o3));
;                 }
	v_lshlrev_b32_e32 v156, 16, v148
	v_and_b32_e32 v157, 0xffff0000, v148
	v_lshlrev_b32_e32 v158, 16, v149
	v_and_b32_e32 v159, 0xffff0000, v149
	v_pk_mul_f32 v[156:157], v[108:109], v[156:157]
	v_pk_mul_f32 v[158:159], v[110:111], v[158:159]
	v_lshlrev_b32_e32 v244, 16, v150
	v_and_b32_e32 v245, 0xffff0000, v150
	v_lshlrev_b32_e32 v246, 16, v151
	v_and_b32_e32 v247, 0xffff0000, v151
	v_pk_mul_f32 v[244:245], v[104:105], v[244:245]
	v_pk_mul_f32 v[246:247], v[106:107], v[246:247]
	v_cvt_pk_bf16_f32 v236, v156, v157
	v_cvt_pk_bf16_f32 v237, v158, v159
	v_cvt_pk_bf16_f32 v238, v244, v245
	v_cvt_pk_bf16_f32 v239, v246, v247
	v_add_u32_e32 v211, 0x20000, v163
	s_nop 3
	v_permlane32_swap_b32_e32 v236, v238
	v_permlane32_swap_b32_e32 v237, v239
	s_nop 3
	v_permlane16_swap_b32_e32 v236, v238
	v_permlane16_swap_b32_e32 v237, v239
	s_nop 3
	global_store_dwordx4 v211, v[236:239], s[6:7]
	v_add_u32_e32 v146, 0x14000, v160
	global_load_dwordx4 v[148:151], v146, s[0:1]
	s_waitcnt lgkmcnt(0)
	v_lshlrev_b32_e32 v156, 16, v164
	v_and_b32_e32 v157, 0xffff0000, v164
	v_lshlrev_b32_e32 v158, 16, v165
	v_and_b32_e32 v159, 0xffff0000, v165
	v_pk_mul_f32 v[156:157], v[100:101], v[156:157]
	v_pk_mul_f32 v[158:159], v[102:103], v[158:159]
	v_lshlrev_b32_e32 v244, 16, v166
	v_and_b32_e32 v245, 0xffff0000, v166
	v_lshlrev_b32_e32 v246, 16, v167
	v_and_b32_e32 v247, 0xffff0000, v167
	v_pk_mul_f32 v[244:245], v[96:97], v[244:245]
	v_pk_mul_f32 v[246:247], v[98:99], v[246:247]
	v_cvt_pk_bf16_f32 v240, v156, v157
	v_cvt_pk_bf16_f32 v241, v158, v159
	v_cvt_pk_bf16_f32 v242, v244, v245
	v_cvt_pk_bf16_f32 v243, v246, v247
	v_add_u32_e32 v210, 0x30000, v163
	s_nop 3
	v_permlane32_swap_b32_e32 v240, v242
	v_permlane32_swap_b32_e32 v241, v243
	s_nop 3
	v_permlane16_swap_b32_e32 v240, v242
	v_permlane16_swap_b32_e32 v241, v243
	s_nop 3
	global_store_dwordx4 v210, v[240:243], s[6:7]
	v_add_u32_e32 v147, 0x16000, v160
	global_load_dwordx4 v[164:167], v147, s[0:1]
	s_waitcnt vmcnt(11)
	v_lshlrev_b32_e32 v156, 16, v172
	v_and_b32_e32 v157, 0xffff0000, v172
	v_lshlrev_b32_e32 v158, 16, v173
	v_and_b32_e32 v159, 0xffff0000, v173
	v_pk_mul_f32 v[156:157], v[92:93], v[156:157]
	v_pk_mul_f32 v[158:159], v[94:95], v[158:159]
	v_lshlrev_b32_e32 v244, 16, v174
	v_and_b32_e32 v245, 0xffff0000, v174
	v_lshlrev_b32_e32 v246, 16, v175
	v_and_b32_e32 v247, 0xffff0000, v175
	v_pk_mul_f32 v[244:245], v[88:89], v[244:245]
	v_pk_mul_f32 v[246:247], v[90:91], v[246:247]
	v_cvt_pk_bf16_f32 v228, v156, v157
	v_cvt_pk_bf16_f32 v229, v158, v159
	v_cvt_pk_bf16_f32 v230, v244, v245
	v_cvt_pk_bf16_f32 v231, v246, v247
	s_nop 3
	v_permlane32_swap_b32_e32 v228, v230
	v_permlane32_swap_b32_e32 v229, v231
	s_nop 3
	v_permlane16_swap_b32_e32 v228, v230
	v_permlane16_swap_b32_e32 v229, v231
	s_nop 3
	global_store_dwordx4 v163, v[228:231], s[6:7] offset:256
	v_add_u32_e32 v146, 0x18000, v160
	global_load_dwordx4 v[172:175], v146, s[0:1]
	s_waitcnt vmcnt(12)
	v_lshlrev_b32_e32 v156, 16, v180
	v_and_b32_e32 v157, 0xffff0000, v180
	v_lshlrev_b32_e32 v158, 16, v181
	v_and_b32_e32 v159, 0xffff0000, v181
	v_pk_mul_f32 v[156:157], v[84:85], v[156:157]
	v_pk_mul_f32 v[158:159], v[86:87], v[158:159]
	v_lshlrev_b32_e32 v244, 16, v182
	v_and_b32_e32 v245, 0xffff0000, v182
	v_lshlrev_b32_e32 v246, 16, v183
	v_and_b32_e32 v247, 0xffff0000, v183
	v_pk_mul_f32 v[244:245], v[80:81], v[244:245]
	v_pk_mul_f32 v[246:247], v[82:83], v[246:247]
	v_cvt_pk_bf16_f32 v232, v156, v157
	v_cvt_pk_bf16_f32 v233, v158, v159
	v_cvt_pk_bf16_f32 v234, v244, v245
	v_cvt_pk_bf16_f32 v235, v246, v247
	v_add_u32_e32 v211, 0x10000, v163
	s_nop 3
	v_permlane32_swap_b32_e32 v232, v234
	v_permlane32_swap_b32_e32 v233, v235
	s_nop 3
	v_permlane16_swap_b32_e32 v232, v234
	v_permlane16_swap_b32_e32 v233, v235
	s_nop 3
	global_store_dwordx4 v211, v[232:235], s[6:7] offset:256
	v_add_u32_e32 v147, 0x1a000, v160
	global_load_dwordx4 v[180:183], v147, s[0:1]
	s_waitcnt vmcnt(13)
	v_lshlrev_b32_e32 v156, 16, v188
	v_and_b32_e32 v157, 0xffff0000, v188
	v_lshlrev_b32_e32 v158, 16, v189
	v_and_b32_e32 v159, 0xffff0000, v189
	v_pk_mul_f32 v[156:157], v[76:77], v[156:157]
	v_pk_mul_f32 v[158:159], v[78:79], v[158:159]
	v_lshlrev_b32_e32 v244, 16, v190
	v_and_b32_e32 v245, 0xffff0000, v190
	v_lshlrev_b32_e32 v246, 16, v191
	v_and_b32_e32 v247, 0xffff0000, v191
	v_pk_mul_f32 v[244:245], v[72:73], v[244:245]
	v_pk_mul_f32 v[246:247], v[74:75], v[246:247]
	v_cvt_pk_bf16_f32 v236, v156, v157
	v_cvt_pk_bf16_f32 v237, v158, v159
	v_cvt_pk_bf16_f32 v238, v244, v245
	v_cvt_pk_bf16_f32 v239, v246, v247
	v_add_u32_e32 v210, 0x20000, v163
	s_nop 3
	v_permlane32_swap_b32_e32 v236, v238
	v_permlane32_swap_b32_e32 v237, v239
	s_nop 3
	v_permlane16_swap_b32_e32 v236, v238
	v_permlane16_swap_b32_e32 v237, v239
	s_nop 3
	global_store_dwordx4 v210, v[236:239], s[6:7] offset:256
	v_add_u32_e32 v146, 0x1c000, v160
	global_load_dwordx4 v[188:191], v146, s[0:1]
	s_waitcnt vmcnt(14)
	v_lshlrev_b32_e32 v156, 16, v212
	v_and_b32_e32 v157, 0xffff0000, v212
	v_lshlrev_b32_e32 v158, 16, v213
	v_and_b32_e32 v159, 0xffff0000, v213
	v_pk_mul_f32 v[156:157], v[68:69], v[156:157]
	v_pk_mul_f32 v[158:159], v[70:71], v[158:159]
	v_lshlrev_b32_e32 v244, 16, v214
	v_and_b32_e32 v245, 0xffff0000, v214
	v_lshlrev_b32_e32 v246, 16, v215
	v_and_b32_e32 v247, 0xffff0000, v215
	v_pk_mul_f32 v[244:245], v[64:65], v[244:245]
	v_pk_mul_f32 v[246:247], v[66:67], v[246:247]
	v_cvt_pk_bf16_f32 v240, v156, v157
	v_cvt_pk_bf16_f32 v241, v158, v159
	v_cvt_pk_bf16_f32 v242, v244, v245
	v_cvt_pk_bf16_f32 v243, v246, v247
	v_add_u32_e32 v211, 0x30000, v163
	s_nop 3
	v_permlane32_swap_b32_e32 v240, v242
	v_permlane32_swap_b32_e32 v241, v243
	s_nop 3
	v_permlane16_swap_b32_e32 v240, v242
	v_permlane16_swap_b32_e32 v241, v243
	s_nop 3
	global_store_dwordx4 v211, v[240:243], s[6:7] offset:256
	v_add_u32_e32 v147, 0x1e000, v160
	global_load_dwordx4 v[212:215], v147, s[0:1]
	s_waitcnt vmcnt(14)
; __device__ __forceinline__ float bflo(unsigned u) { return __uint_as_float(u << 16); }
; __device__ __forceinline__ float bfhi(unsigned u) { return __uint_as_float(u & 0xFFFF0000u); }
; __device__ __forceinline__ void phaseE(const Params& p, int layer) {
;     ...
; #pragma unroll
;               for (int mm = 0; mm < 2; mm++) {
;                 const int m = mh * 2 + mm;
;                 g4[mm] = *(const uint4*)(gsb + ((ai * 2 + bj) * 4 + m) * 8192 + gs_lane);
;                 if (br) {
; #pragma unroll
;                   for (int n = 0; n < 2; n++)
;                     old[mm][n] = *(const uint2*)(mb + ((size_t)(ai * 128 + m * 16) * 2048 + bj * 128 + n * 16) * 2 + lane_m);
;                 }
;               }
; #pragma unroll
;               for (int mm = 0; mm < 2; mm++) {
;                 const int m = mh * 2 + mm;
;                 const unsigned gq[4] = {g4[mm].x, g4[mm].y, g4[mm].z, g4[mm].w};
; #pragma unroll
;                 for (int n = 0; n < 2; n++) {
;                   f32x4 v = acc[ai][bj][m][n];
;                   float o0 = bflo(gq[2 * n]) * v[0], o1 = bfhi(gq[2 * n]) * v[1], o2 = bflo(gq[2 * n + 1]) * v[2], o3 = bfhi(gq[2 * n + 1]) * v[3];
;                   char* mp = mb + ((size_t)(ai * 128 + m * 16) * 2048 + bj * 128 + n * 16) * 2 + lane_m;
;                   if (br) { o0 += bflo(old[mm][n].x); o1 += bfhi(old[mm][n].x); o2 += bflo(old[mm][n].y); o3 += bfhi(old[mm][n].y); }
;                   *(uint2*)mp = make_uint2(pk2(o0, o1), pk2(o2, o3));
;                 }
	v_lshlrev_b32_e32 v156, 16, v128
	v_and_b32_e32 v157, 0xffff0000, v128
	v_lshlrev_b32_e32 v158, 16, v129
	v_and_b32_e32 v159, 0xffff0000, v129
	v_pk_mul_f32 v[156:157], v[60:61], v[156:157]
	v_pk_mul_f32 v[158:159], v[62:63], v[158:159]
	v_lshlrev_b32_e32 v244, 16, v130
	v_and_b32_e32 v245, 0xffff0000, v130
	v_lshlrev_b32_e32 v246, 16, v131
	v_and_b32_e32 v247, 0xffff0000, v131
	v_pk_mul_f32 v[244:245], v[56:57], v[244:245]
	v_pk_mul_f32 v[246:247], v[58:59], v[246:247]
	v_cvt_pk_bf16_f32 v228, v156, v157
	v_cvt_pk_bf16_f32 v229, v158, v159
	v_cvt_pk_bf16_f32 v230, v244, v245
	v_cvt_pk_bf16_f32 v231, v246, v247
	v_add_u32_e32 v210, 0x80000, v163
	s_nop 3
	v_permlane32_swap_b32_e32 v228, v230
	v_permlane32_swap_b32_e32 v229, v231
	s_nop 3
	v_permlane16_swap_b32_e32 v228, v230
	v_permlane16_swap_b32_e32 v229, v231
	s_nop 3
	global_store_dwordx4 v210, v[228:231], s[6:7]
	s_waitcnt vmcnt(13)
	v_lshlrev_b32_e32 v156, 16, v136
	v_and_b32_e32 v157, 0xffff0000, v136
	v_lshlrev_b32_e32 v158, 16, v137
	v_and_b32_e32 v159, 0xffff0000, v137
	v_pk_mul_f32 v[156:157], v[52:53], v[156:157]
	v_pk_mul_f32 v[158:159], v[54:55], v[158:159]
	v_lshlrev_b32_e32 v244, 16, v138
	v_and_b32_e32 v245, 0xffff0000, v138
	v_lshlrev_b32_e32 v246, 16, v139
	v_and_b32_e32 v247, 0xffff0000, v139
	v_pk_mul_f32 v[244:245], v[48:49], v[244:245]
	v_pk_mul_f32 v[246:247], v[50:51], v[246:247]
	v_cvt_pk_bf16_f32 v232, v156, v157
	v_cvt_pk_bf16_f32 v233, v158, v159
	v_cvt_pk_bf16_f32 v234, v244, v245
	v_cvt_pk_bf16_f32 v235, v246, v247
	v_add_u32_e32 v211, 0x90000, v163
	s_nop 3
	v_permlane32_swap_b32_e32 v232, v234
	v_permlane32_swap_b32_e32 v233, v235
	s_nop 3
	v_permlane16_swap_b32_e32 v232, v234
	v_permlane16_swap_b32_e32 v233, v235
	s_nop 3
	global_store_dwordx4 v211, v[232:235], s[6:7]
	s_waitcnt vmcnt(12)
	v_lshlrev_b32_e32 v156, 16, v148
	v_and_b32_e32 v157, 0xffff0000, v148
	v_lshlrev_b32_e32 v158, 16, v149
	v_and_b32_e32 v159, 0xffff0000, v149
	v_pk_mul_f32 v[156:157], v[44:45], v[156:157]
	v_pk_mul_f32 v[158:159], v[46:47], v[158:159]
	v_lshlrev_b32_e32 v244, 16, v150
	v_and_b32_e32 v245, 0xffff0000, v150
	v_lshlrev_b32_e32 v246, 16, v151
	v_and_b32_e32 v247, 0xffff0000, v151
	v_pk_mul_f32 v[244:245], v[40:41], v[244:245]
	v_pk_mul_f32 v[246:247], v[42:43], v[246:247]
	v_cvt_pk_bf16_f32 v236, v156, v157
	v_cvt_pk_bf16_f32 v237, v158, v159
	v_cvt_pk_bf16_f32 v238, v244, v245
	v_cvt_pk_bf16_f32 v239, v246, v247
	v_add_u32_e32 v210, 0xa0000, v163
	s_nop 3
	v_permlane32_swap_b32_e32 v236, v238
	v_permlane32_swap_b32_e32 v237, v239
	s_nop 3
	v_permlane16_swap_b32_e32 v236, v238
	v_permlane16_swap_b32_e32 v237, v239
	s_nop 3
	global_store_dwordx4 v210, v[236:239], s[6:7]
	s_waitcnt vmcnt(11)
	v_lshlrev_b32_e32 v156, 16, v164
	v_and_b32_e32 v157, 0xffff0000, v164
	v_lshlrev_b32_e32 v158, 16, v165
	v_and_b32_e32 v159, 0xffff0000, v165
	v_pk_mul_f32 v[156:157], v[36:37], v[156:157]
	v_pk_mul_f32 v[158:159], v[38:39], v[158:159]
	v_lshlrev_b32_e32 v244, 16, v166
	v_and_b32_e32 v245, 0xffff0000, v166
	v_lshlrev_b32_e32 v246, 16, v167
	v_and_b32_e32 v247, 0xffff0000, v167
	v_pk_mul_f32 v[244:245], v[32:33], v[244:245]
	v_pk_mul_f32 v[246:247], v[34:35], v[246:247]
	v_cvt_pk_bf16_f32 v240, v156, v157
	v_cvt_pk_bf16_f32 v241, v158, v159
	v_cvt_pk_bf16_f32 v242, v244, v245
	v_cvt_pk_bf16_f32 v243, v246, v247
	v_add_u32_e32 v211, 0xb0000, v163
	s_nop 3
	v_permlane32_swap_b32_e32 v240, v242
	v_permlane32_swap_b32_e32 v241, v243
	s_nop 3
	v_permlane16_swap_b32_e32 v240, v242
	v_permlane16_swap_b32_e32 v241, v243
	s_nop 3
	global_store_dwordx4 v211, v[240:243], s[6:7]
	s_waitcnt vmcnt(10)
; __device__ __forceinline__ float bflo(unsigned u) { return __uint_as_float(u << 16); }
; __device__ __forceinline__ float bfhi(unsigned u) { return __uint_as_float(u & 0xFFFF0000u); }
; __device__ __forceinline__ void phaseE(const Params& p, int layer) {
;     ...
; #pragma unroll
;               for (int mm = 0; mm < 2; mm++) {
;                 const int m = mh * 2 + mm;
;                 g4[mm] = *(const uint4*)(gsb + ((ai * 2 + bj) * 4 + m) * 8192 + gs_lane);
;                 if (br) {
; #pragma unroll
;                   for (int n = 0; n < 2; n++)
;                     old[mm][n] = *(const uint2*)(mb + ((size_t)(ai * 128 + m * 16) * 2048 + bj * 128 + n * 16) * 2 + lane_m);
;                 }
;               }
; #pragma unroll
;               for (int mm = 0; mm < 2; mm++) {
;                 const int m = mh * 2 + mm;
;                 const unsigned gq[4] = {g4[mm].x, g4[mm].y, g4[mm].z, g4[mm].w};
; #pragma unroll
;                 for (int n = 0; n < 2; n++) {
;                   f32x4 v = acc[ai][bj][m][n];
;                   float o0 = bflo(gq[2 * n]) * v[0], o1 = bfhi(gq[2 * n]) * v[1], o2 = bflo(gq[2 * n + 1]) * v[2], o3 = bfhi(gq[2 * n + 1]) * v[3];
;                   char* mp = mb + ((size_t)(ai * 128 + m * 16) * 2048 + bj * 128 + n * 16) * 2 + lane_m;
;                   if (br) { o0 += bflo(old[mm][n].x); o1 += bfhi(old[mm][n].x); o2 += bflo(old[mm][n].y); o3 += bfhi(old[mm][n].y); }
;                   *(uint2*)mp = make_uint2(pk2(o0, o1), pk2(o2, o3));
;                 }
	v_lshlrev_b32_e32 v156, 16, v172
	v_and_b32_e32 v157, 0xffff0000, v172
	v_lshlrev_b32_e32 v158, 16, v173
	v_and_b32_e32 v159, 0xffff0000, v173
	v_pk_mul_f32 v[156:157], v[28:29], v[156:157]
	v_pk_mul_f32 v[158:159], v[30:31], v[158:159]
	v_lshlrev_b32_e32 v244, 16, v174
	v_and_b32_e32 v245, 0xffff0000, v174
	v_lshlrev_b32_e32 v246, 16, v175
	v_and_b32_e32 v247, 0xffff0000, v175
	v_pk_mul_f32 v[244:245], v[24:25], v[244:245]
	v_pk_mul_f32 v[246:247], v[26:27], v[246:247]
	v_cvt_pk_bf16_f32 v228, v156, v157
	v_cvt_pk_bf16_f32 v229, v158, v159
	v_cvt_pk_bf16_f32 v230, v244, v245
	v_cvt_pk_bf16_f32 v231, v246, v247
	v_add_u32_e32 v210, 0x80000, v163
	s_nop 3
	v_permlane32_swap_b32_e32 v228, v230
	v_permlane32_swap_b32_e32 v229, v231
	s_nop 3
	v_permlane16_swap_b32_e32 v228, v230
	v_permlane16_swap_b32_e32 v229, v231
	s_nop 3
	global_store_dwordx4 v210, v[228:231], s[6:7] offset:256
	s_waitcnt vmcnt(9)
	v_lshlrev_b32_e32 v156, 16, v180
	v_and_b32_e32 v157, 0xffff0000, v180
	v_lshlrev_b32_e32 v158, 16, v181
	v_and_b32_e32 v159, 0xffff0000, v181
	v_pk_mul_f32 v[156:157], v[20:21], v[156:157]
	v_pk_mul_f32 v[158:159], v[22:23], v[158:159]
	v_lshlrev_b32_e32 v244, 16, v182
	v_and_b32_e32 v245, 0xffff0000, v182
	v_lshlrev_b32_e32 v246, 16, v183
	v_and_b32_e32 v247, 0xffff0000, v183
	v_pk_mul_f32 v[244:245], v[16:17], v[244:245]
	v_pk_mul_f32 v[246:247], v[18:19], v[246:247]
	v_cvt_pk_bf16_f32 v232, v156, v157
	v_cvt_pk_bf16_f32 v233, v158, v159
	v_cvt_pk_bf16_f32 v234, v244, v245
	v_cvt_pk_bf16_f32 v235, v246, v247
	v_add_u32_e32 v211, 0x90000, v163
	s_nop 3
	v_permlane32_swap_b32_e32 v232, v234
	v_permlane32_swap_b32_e32 v233, v235
	s_nop 3
	v_permlane16_swap_b32_e32 v232, v234
	v_permlane16_swap_b32_e32 v233, v235
	s_nop 3
	global_store_dwordx4 v211, v[232:235], s[6:7] offset:256
	s_waitcnt vmcnt(8)
	v_lshlrev_b32_e32 v156, 16, v188
	v_and_b32_e32 v157, 0xffff0000, v188
	v_lshlrev_b32_e32 v158, 16, v189
	v_and_b32_e32 v159, 0xffff0000, v189
	v_pk_mul_f32 v[156:157], v[12:13], v[156:157]
	v_pk_mul_f32 v[158:159], v[14:15], v[158:159]
	v_lshlrev_b32_e32 v244, 16, v190
	v_and_b32_e32 v245, 0xffff0000, v190
	v_lshlrev_b32_e32 v246, 16, v191
	v_and_b32_e32 v247, 0xffff0000, v191
	v_pk_mul_f32 v[244:245], v[8:9], v[244:245]
	v_pk_mul_f32 v[246:247], v[10:11], v[246:247]
	v_cvt_pk_bf16_f32 v236, v156, v157
	v_cvt_pk_bf16_f32 v237, v158, v159
	v_cvt_pk_bf16_f32 v238, v244, v245
	v_cvt_pk_bf16_f32 v239, v246, v247
	v_add_u32_e32 v210, 0xa0000, v163
	s_nop 3
	v_permlane32_swap_b32_e32 v236, v238
	v_permlane32_swap_b32_e32 v237, v239
	s_nop 3
	v_permlane16_swap_b32_e32 v236, v238
	v_permlane16_swap_b32_e32 v237, v239
	s_nop 3
	global_store_dwordx4 v210, v[236:239], s[6:7] offset:256
	s_waitcnt vmcnt(7)
	v_lshlrev_b32_e32 v156, 16, v212
	v_and_b32_e32 v157, 0xffff0000, v212
	v_lshlrev_b32_e32 v158, 16, v213
	v_and_b32_e32 v159, 0xffff0000, v213
	v_pk_mul_f32 v[156:157], v[4:5], v[156:157]
	v_pk_mul_f32 v[158:159], v[6:7], v[158:159]
	v_lshlrev_b32_e32 v244, 16, v214
	v_and_b32_e32 v245, 0xffff0000, v214
	v_lshlrev_b32_e32 v246, 16, v215
	v_and_b32_e32 v247, 0xffff0000, v215
	v_pk_mul_f32 v[244:245], v[0:1], v[244:245]
	v_pk_mul_f32 v[246:247], v[2:3], v[246:247]
	v_cvt_pk_bf16_f32 v240, v156, v157
	v_cvt_pk_bf16_f32 v241, v158, v159
	v_cvt_pk_bf16_f32 v242, v244, v245
	v_cvt_pk_bf16_f32 v243, v246, v247
	v_add_u32_e32 v211, 0xb0000, v163
	s_nop 3
	v_permlane32_swap_b32_e32 v240, v242
	v_permlane32_swap_b32_e32 v241, v243
	s_nop 3
	v_permlane16_swap_b32_e32 v240, v242
	v_permlane16_swap_b32_e32 v241, v243
	s_nop 3
	global_store_dwordx4 v211, v[240:243], s[6:7] offset:256
	s_branch .LBB0_2313
